# grid barriers: acquire-side L1 invalidate issued before polling (all other waves are drained and parked at the workgroup barrier, polls bypass L1), leader invalidates right after its L2 write-back
# speedup vs baseline: 1.0092x; 1.0062x over previous
; __device__ __forceinline__ unsigned xb_ld(unsigned* p)              { return __hip_atomic_load(p, __ATOMIC_RELAXED, __HIP_MEMORY_SCOPE_AGENT); }
; __device__ __forceinline__ unsigned xb_add(unsigned* p, unsigned v) { return __hip_atomic_fetch_add(p, v, __ATOMIC_RELAXED, __HIP_MEMORY_SCOPE_AGENT); }
; #define XB_SPIN(cond, bar) do { unsigned _sp = 0; while (cond) { __builtin_amdgcn_s_sleep(1); \
;     if ((++_sp & 255u) == 0u) { if (xb_ld(&(bar)[XB_TMO])) break; if (_sp > XB_SPIN_CAP) { atomicAdd(&(bar)[XB_TMO], 1u); break; } } } } while (0)
; __device__ __forceinline__ void xcd_barrier(const XcdBarrier& b) {
;     ...
;         const unsigned old = xb_add(&bar[XB_XSUB(b.x)], 1u);
;         const unsigned gen = old / nloc;
;         if (old + 1u == (gen + 1u) * nloc) {
;             __builtin_amdgcn_fence(__ATOMIC_RELEASE, "agent");
;             asm volatile("s_waitcnt vmcnt(0)" ::: "memory");
;             const unsigned og = xb_add(&bar[XB_TOP], 1u);
;             const unsigned tg = og / nx;
;             if (og + 1u == (tg + 1u) * nx) xb_add(&bar[XB_TOPGEN], 1u);
;             else XB_SPIN(xb_ld(&bar[XB_TOPGEN]) == tg, bar);
;             __builtin_amdgcn_fence(__ATOMIC_ACQUIRE, "agent");
;             xb_add(&bar[XB_XGEN(b.x)], 1u);
;             asm volatile("s_waitcnt vmcnt(0)" ::: "memory");
;         } else {
;             XB_SPIN(xb_ld(&bar[XB_XGEN(b.x)]) == gen, bar);
.LBB0_149:
	s_or_b64 exec, exec, s[10:11]
	v_cvt_f32_u32_e32 v4, v2
	s_waitcnt vmcnt(0)
	v_readfirstlane_b32 s8, v3
	v_sub_u32_e32 v3, 0, v2
	v_rcp_iflag_f32_e32 v4, v4
	v_add_u32_e32 v5, s8, v1
	v_mul_f32_e32 v4, 0x4f7ffffe, v4
	v_cvt_u32_f32_e32 v4, v4
	v_mul_lo_u32 v1, v3, v4
	v_mul_hi_u32 v1, v4, v1
	v_add_u32_e32 v1, v4, v1
	v_mul_hi_u32 v1, v5, v1
	v_mul_lo_u32 v3, v1, v2
	v_sub_u32_e32 v3, v5, v3
	v_add_u32_e32 v4, 1, v1
	v_cmp_ge_u32_e32 vcc, v3, v2
	s_nop 1
	v_cndmask_b32_e32 v1, v1, v4, vcc
	v_sub_u32_e32 v4, v3, v2
	v_cndmask_b32_e32 v3, v3, v4, vcc
	v_add_u32_e32 v4, 1, v1
	v_cmp_ge_u32_e32 vcc, v3, v2
	v_add_u32_e32 v3, 1, v5
	s_nop 0
	v_cndmask_b32_e32 v1, v1, v4, vcc
	v_mul_lo_u32 v4, v2, v1
	v_add_u32_e32 v2, v4, v2
	v_cmp_ne_u32_e32 vcc, v3, v2
	s_and_saveexec_b64 s[8:9], vcc
	s_xor_b64 s[8:9], exec, s[8:9]
	s_cbranch_execz .LBB0_163
	s_waitcnt lgkmcnt(0)
	v_mov_b32_e32 v0, 0x2000
	buffer_inv sc1
	global_load_dword v0, v0, s[6:7] offset:1024 sc1
	s_add_u32 s18, s6, 0x2400
	s_addc_u32 s19, s7, 0
	s_waitcnt vmcnt(0)
	v_cmp_eq_u32_e32 vcc, v0, v1
	s_and_saveexec_b64 s[10:11], vcc
	s_cbranch_execz .LBB0_162
	s_add_u32 s12, s70, 0x2300200
	s_addc_u32 s13, s71, 0
	s_mov_b32 s14, 1
	s_mov_b64 s[20:21], 0
	v_mov_b32_e32 v0, 0
	s_branch .LBB0_153

; __device__ __forceinline__ unsigned xb_ld(unsigned* p)              { return __hip_atomic_load(p, __ATOMIC_RELAXED, __HIP_MEMORY_SCOPE_AGENT); }
; __device__ __forceinline__ unsigned xb_add(unsigned* p, unsigned v) { return __hip_atomic_fetch_add(p, v, __ATOMIC_RELAXED, __HIP_MEMORY_SCOPE_AGENT); }
; #define XB_SPIN(cond, bar) do { unsigned _sp = 0; while (cond) { __builtin_amdgcn_s_sleep(1); \
;     if ((++_sp & 255u) == 0u) { if (xb_ld(&(bar)[XB_TMO])) break; if (_sp > XB_SPIN_CAP) { atomicAdd(&(bar)[XB_TMO], 1u); break; } } } } while (0)
; __device__ __forceinline__ void xcd_barrier(const XcdBarrier& b) {
;     ...
;             __builtin_amdgcn_fence(__ATOMIC_RELEASE, "agent");
;             asm volatile("s_waitcnt vmcnt(0)" ::: "memory");
;             const unsigned og = xb_add(&bar[XB_TOP], 1u);
;     ...
;         } else {
;             XB_SPIN(xb_ld(&bar[XB_XGEN(b.x)]) == gen, bar);
;             __builtin_amdgcn_fence(__ATOMIC_ACQUIRE, "agent");
;             asm volatile("s_waitcnt vmcnt(0)" ::: "memory");
.LBB0_162:
	s_or_b64 exec, exec, s[10:11]
	s_waitcnt vmcnt(0)
	s_waitcnt vmcnt(0)
.LBB0_163:
	s_andn2_saveexec_b64 s[8:9], s[8:9]
	s_cbranch_execz .LBB0_183
	s_mov_b64 s[8:9], exec
	buffer_wbl2 sc1
	s_waitcnt lgkmcnt(0)
	s_waitcnt vmcnt(0)
	buffer_inv sc1
	v_mbcnt_lo_u32_b32 v1, s8, 0
	v_mbcnt_hi_u32_b32 v1, s9, v1
	v_cmp_eq_u32_e32 vcc, 0, v1
	s_and_saveexec_b64 s[10:11], vcc
	s_cbranch_execz .LBB0_166
	s_bcnt1_i32_b64 s8, s[8:9]
	v_mov_b32_e32 v2, 0x2303000
	v_mov_b32_e32 v3, s8
	global_atomic_add v2, v2, v3, s[70:71] offset:1024 sc0

; __device__ __forceinline__ unsigned xb_ld(unsigned* p)              { return __hip_atomic_load(p, __ATOMIC_RELAXED, __HIP_MEMORY_SCOPE_AGENT); }
; __device__ __forceinline__ unsigned xb_add(unsigned* p, unsigned v) { return __hip_atomic_fetch_add(p, v, __ATOMIC_RELAXED, __HIP_MEMORY_SCOPE_AGENT); }
; #define XB_SPIN(cond, bar) do { unsigned _sp = 0; while (cond) { __builtin_amdgcn_s_sleep(1); \
;     if ((++_sp & 255u) == 0u) { if (xb_ld(&(bar)[XB_TMO])) break; if (_sp > XB_SPIN_CAP) { atomicAdd(&(bar)[XB_TMO], 1u); break; } } } } while (0)
; __device__ __forceinline__ void xcd_barrier(const XcdBarrier& b) {
;     ...
;             else XB_SPIN(xb_ld(&bar[XB_TOPGEN]) == tg, bar);
;             __builtin_amdgcn_fence(__ATOMIC_ACQUIRE, "agent");
;             xb_add(&bar[XB_XGEN(b.x)], 1u);
.LBB0_180:
	s_or_b64 exec, exec, s[8:9]
	s_mov_b64 s[8:9], exec
	v_mbcnt_lo_u32_b32 v0, s8, 0
	v_mbcnt_hi_u32_b32 v0, s9, v0
	v_cmp_eq_u32_e32 vcc, 0, v0
	s_waitcnt vmcnt(0)
	s_and_saveexec_b64 s[10:11], vcc
	s_cbranch_execz .LBB0_182
	s_bcnt1_i32_b64 s8, s[8:9]
	v_mov_b32_e32 v0, 0x2000
	v_mov_b32_e32 v1, s8
	global_atomic_add v0, v1, s[6:7] offset:1024

; __device__ __forceinline__ unsigned xb_ld(unsigned* p)              { return __hip_atomic_load(p, __ATOMIC_RELAXED, __HIP_MEMORY_SCOPE_AGENT); }
; __device__ __forceinline__ unsigned xb_add(unsigned* p, unsigned v) { return __hip_atomic_fetch_add(p, v, __ATOMIC_RELAXED, __HIP_MEMORY_SCOPE_AGENT); }
; #define XB_SPIN(cond, bar) do { unsigned _sp = 0; while (cond) { __builtin_amdgcn_s_sleep(1); \
;     if ((++_sp & 255u) == 0u) { if (xb_ld(&(bar)[XB_TMO])) break; if (_sp > XB_SPIN_CAP) { atomicAdd(&(bar)[XB_TMO], 1u); break; } } } } while (0)
; __device__ __forceinline__ void xcd_barrier(const XcdBarrier& b) {
;     ...
;         const unsigned old = xb_add(&bar[XB_XSUB(b.x)], 1u);
;         const unsigned gen = old / nloc;
;         if (old + 1u == (gen + 1u) * nloc) {
;             __builtin_amdgcn_fence(__ATOMIC_RELEASE, "agent");
;             asm volatile("s_waitcnt vmcnt(0)" ::: "memory");
;             const unsigned og = xb_add(&bar[XB_TOP], 1u);
;             const unsigned tg = og / nx;
;             if (og + 1u == (tg + 1u) * nx) xb_add(&bar[XB_TOPGEN], 1u);
;             else XB_SPIN(xb_ld(&bar[XB_TOPGEN]) == tg, bar);
;             __builtin_amdgcn_fence(__ATOMIC_ACQUIRE, "agent");
;             xb_add(&bar[XB_XGEN(b.x)], 1u);
;             asm volatile("s_waitcnt vmcnt(0)" ::: "memory");
;         } else {
;             XB_SPIN(xb_ld(&bar[XB_XGEN(b.x)]) == gen, bar);
.LBB0_242:
	s_or_b64 exec, exec, s[8:9]
	v_cvt_f32_u32_e32 v4, v2
	s_waitcnt vmcnt(0)
	v_readfirstlane_b32 s6, v3
	v_sub_u32_e32 v3, 0, v2
	v_rcp_iflag_f32_e32 v4, v4
	v_add_u32_e32 v5, s6, v1
	v_mul_f32_e32 v4, 0x4f7ffffe, v4
	v_cvt_u32_f32_e32 v4, v4
	v_mul_lo_u32 v1, v3, v4
	v_mul_hi_u32 v1, v4, v1
	v_add_u32_e32 v1, v4, v1
	v_mul_hi_u32 v1, v5, v1
	v_mul_lo_u32 v3, v1, v2
	v_sub_u32_e32 v3, v5, v3
	v_add_u32_e32 v4, 1, v1
	v_cmp_ge_u32_e32 vcc, v3, v2
	s_nop 1
	v_cndmask_b32_e32 v1, v1, v4, vcc
	v_sub_u32_e32 v4, v3, v2
	v_cndmask_b32_e32 v3, v3, v4, vcc
	v_add_u32_e32 v4, 1, v1
	v_cmp_ge_u32_e32 vcc, v3, v2
	v_add_u32_e32 v3, 1, v5
	s_nop 0
	v_cndmask_b32_e32 v1, v1, v4, vcc
	v_mul_lo_u32 v4, v2, v1
	v_add_u32_e32 v2, v4, v2
	v_cmp_ne_u32_e32 vcc, v3, v2
	s_and_saveexec_b64 s[6:7], vcc
	s_xor_b64 s[6:7], exec, s[6:7]
	s_cbranch_execz .LBB0_256
	s_waitcnt lgkmcnt(0)
	v_mov_b32_e32 v0, 0x2000
	buffer_inv sc1
	global_load_dword v0, v0, s[4:5] offset:1024 sc1
	s_add_u32 s12, s4, 0x2400
	s_addc_u32 s13, s5, 0
	s_waitcnt vmcnt(0)
	v_cmp_eq_u32_e32 vcc, v0, v1
	s_and_saveexec_b64 s[8:9], vcc
	s_cbranch_execz .LBB0_255
	s_add_u32 s10, s70, 0x2300200
	s_addc_u32 s11, s71, 0
	s_mov_b32 s14, 1
	s_mov_b64 s[18:19], 0
	v_mov_b32_e32 v0, 0
	s_branch .LBB0_246

; __device__ __forceinline__ unsigned xb_ld(unsigned* p)              { return __hip_atomic_load(p, __ATOMIC_RELAXED, __HIP_MEMORY_SCOPE_AGENT); }
; __device__ __forceinline__ unsigned xb_add(unsigned* p, unsigned v) { return __hip_atomic_fetch_add(p, v, __ATOMIC_RELAXED, __HIP_MEMORY_SCOPE_AGENT); }
; #define XB_SPIN(cond, bar) do { unsigned _sp = 0; while (cond) { __builtin_amdgcn_s_sleep(1); \
;     if ((++_sp & 255u) == 0u) { if (xb_ld(&(bar)[XB_TMO])) break; if (_sp > XB_SPIN_CAP) { atomicAdd(&(bar)[XB_TMO], 1u); break; } } } } while (0)
; __device__ __forceinline__ void xcd_barrier(const XcdBarrier& b) {
;     ...
;             __builtin_amdgcn_fence(__ATOMIC_RELEASE, "agent");
;             asm volatile("s_waitcnt vmcnt(0)" ::: "memory");
;             const unsigned og = xb_add(&bar[XB_TOP], 1u);
;     ...
;         } else {
;             XB_SPIN(xb_ld(&bar[XB_XGEN(b.x)]) == gen, bar);
;             __builtin_amdgcn_fence(__ATOMIC_ACQUIRE, "agent");
;             asm volatile("s_waitcnt vmcnt(0)" ::: "memory");
.LBB0_255:
	s_or_b64 exec, exec, s[8:9]
	s_waitcnt vmcnt(0)
	s_waitcnt vmcnt(0)
.LBB0_256:
	s_andn2_saveexec_b64 s[6:7], s[6:7]
	s_cbranch_execz .LBB0_276
	s_mov_b64 s[6:7], exec
	buffer_wbl2 sc1
	s_waitcnt lgkmcnt(0)
	s_waitcnt vmcnt(0)
	buffer_inv sc1
	v_mbcnt_lo_u32_b32 v1, s6, 0
	v_mbcnt_hi_u32_b32 v1, s7, v1
	v_cmp_eq_u32_e32 vcc, 0, v1
	s_and_saveexec_b64 s[8:9], vcc
	s_cbranch_execz .LBB0_259
	s_bcnt1_i32_b64 s6, s[6:7]
	v_mov_b32_e32 v2, 0x2303000
	v_mov_b32_e32 v3, s6
	global_atomic_add v2, v2, v3, s[70:71] offset:1024 sc0

; __device__ __forceinline__ unsigned xb_ld(unsigned* p)              { return __hip_atomic_load(p, __ATOMIC_RELAXED, __HIP_MEMORY_SCOPE_AGENT); }
; __device__ __forceinline__ unsigned xb_add(unsigned* p, unsigned v) { return __hip_atomic_fetch_add(p, v, __ATOMIC_RELAXED, __HIP_MEMORY_SCOPE_AGENT); }
; #define XB_SPIN(cond, bar) do { unsigned _sp = 0; while (cond) { __builtin_amdgcn_s_sleep(1); \
;     if ((++_sp & 255u) == 0u) { if (xb_ld(&(bar)[XB_TMO])) break; if (_sp > XB_SPIN_CAP) { atomicAdd(&(bar)[XB_TMO], 1u); break; } } } } while (0)
; __device__ __forceinline__ void xcd_barrier(const XcdBarrier& b) {
;     ...
;             else XB_SPIN(xb_ld(&bar[XB_TOPGEN]) == tg, bar);
;             __builtin_amdgcn_fence(__ATOMIC_ACQUIRE, "agent");
;             xb_add(&bar[XB_XGEN(b.x)], 1u);
.LBB0_273:
	s_or_b64 exec, exec, s[6:7]
	s_mov_b64 s[6:7], exec
	v_mbcnt_lo_u32_b32 v0, s6, 0
	v_mbcnt_hi_u32_b32 v0, s7, v0
	v_cmp_eq_u32_e32 vcc, 0, v0
	s_waitcnt vmcnt(0)
	s_and_saveexec_b64 s[8:9], vcc
	s_cbranch_execz .LBB0_275
	s_bcnt1_i32_b64 s6, s[6:7]
	v_mov_b32_e32 v0, 0x2000
	v_mov_b32_e32 v1, s6
	global_atomic_add v0, v1, s[4:5] offset:1024

; __device__ __forceinline__ unsigned xb_ld(unsigned* p)              { return __hip_atomic_load(p, __ATOMIC_RELAXED, __HIP_MEMORY_SCOPE_AGENT); }
; __device__ __forceinline__ unsigned xb_add(unsigned* p, unsigned v) { return __hip_atomic_fetch_add(p, v, __ATOMIC_RELAXED, __HIP_MEMORY_SCOPE_AGENT); }
; #define XB_SPIN(cond, bar) do { unsigned _sp = 0; while (cond) { __builtin_amdgcn_s_sleep(1); \
;     if ((++_sp & 255u) == 0u) { if (xb_ld(&(bar)[XB_TMO])) break; if (_sp > XB_SPIN_CAP) { atomicAdd(&(bar)[XB_TMO], 1u); break; } } } } while (0)
; __device__ __forceinline__ void xcd_barrier(const XcdBarrier& b) {
;     ...
;         const unsigned old = xb_add(&bar[XB_XSUB(b.x)], 1u);
;         const unsigned gen = old / nloc;
;         if (old + 1u == (gen + 1u) * nloc) {
;             __builtin_amdgcn_fence(__ATOMIC_RELEASE, "agent");
;             asm volatile("s_waitcnt vmcnt(0)" ::: "memory");
;             const unsigned og = xb_add(&bar[XB_TOP], 1u);
;             const unsigned tg = og / nx;
;             if (og + 1u == (tg + 1u) * nx) xb_add(&bar[XB_TOPGEN], 1u);
;             else XB_SPIN(xb_ld(&bar[XB_TOPGEN]) == tg, bar);
;             __builtin_amdgcn_fence(__ATOMIC_ACQUIRE, "agent");
;             xb_add(&bar[XB_XGEN(b.x)], 1u);
;             asm volatile("s_waitcnt vmcnt(0)" ::: "memory");
;         } else {
;             XB_SPIN(xb_ld(&bar[XB_XGEN(b.x)]) == gen, bar);
.LBB0_785:
	s_or_b64 exec, exec, s[10:11]
	v_cvt_f32_u32_e32 v4, v2
	s_waitcnt vmcnt(0)
	v_readfirstlane_b32 s3, v3
	v_sub_u32_e32 v3, 0, v2
	v_rcp_iflag_f32_e32 v4, v4
	v_add_u32_e32 v5, s3, v1
	v_mul_f32_e32 v4, 0x4f7ffffe, v4
	v_cvt_u32_f32_e32 v4, v4
	v_mul_lo_u32 v1, v3, v4
	v_mul_hi_u32 v1, v4, v1
	v_add_u32_e32 v1, v4, v1
	v_mul_hi_u32 v1, v5, v1
	v_mul_lo_u32 v3, v1, v2
	v_sub_u32_e32 v3, v5, v3
	v_add_u32_e32 v4, 1, v1
	v_cmp_ge_u32_e32 vcc, v3, v2
	s_nop 1
	v_cndmask_b32_e32 v1, v1, v4, vcc
	v_sub_u32_e32 v4, v3, v2
	v_cndmask_b32_e32 v3, v3, v4, vcc
	v_add_u32_e32 v4, 1, v1
	v_cmp_ge_u32_e32 vcc, v3, v2
	v_add_u32_e32 v3, 1, v5
	s_nop 0
	v_cndmask_b32_e32 v1, v1, v4, vcc
	v_mul_lo_u32 v4, v2, v1
	v_add_u32_e32 v2, v4, v2
	v_cmp_ne_u32_e32 vcc, v3, v2
	s_and_saveexec_b64 s[8:9], vcc
	s_xor_b64 s[8:9], exec, s[8:9]
	s_cbranch_execz .LBB0_799
	s_waitcnt lgkmcnt(0)
	v_mov_b32_e32 v0, 0x2000
	buffer_inv sc1
	global_load_dword v0, v0, s[6:7] offset:1024 sc1
	s_add_u32 s14, s6, 0x2400
	s_addc_u32 s15, s7, 0
	s_waitcnt vmcnt(0)
	v_cmp_eq_u32_e32 vcc, v0, v1
	s_and_saveexec_b64 s[10:11], vcc
	s_cbranch_execz .LBB0_798
	s_add_u32 s12, s70, 0x2300200
	s_addc_u32 s13, s71, 0
	s_mov_b32 s3, 1
	s_mov_b64 s[18:19], 0
	v_mov_b32_e32 v0, 0
	s_branch .LBB0_789

; __device__ __forceinline__ unsigned xb_add(unsigned* p, unsigned v) { return __hip_atomic_fetch_add(p, v, __ATOMIC_RELAXED, __HIP_MEMORY_SCOPE_AGENT); }
; __device__ __forceinline__ void xcd_barrier(const XcdBarrier& b) {
;     ...
;             __builtin_amdgcn_fence(__ATOMIC_RELEASE, "agent");
;             asm volatile("s_waitcnt vmcnt(0)" ::: "memory");
;             const unsigned og = xb_add(&bar[XB_TOP], 1u);
.LBB0_799:
	s_andn2_saveexec_b64 s[8:9], s[8:9]
	s_cbranch_execz .LBB0_819
	s_mov_b64 s[8:9], exec
	buffer_wbl2 sc1
	s_waitcnt lgkmcnt(0)
	s_waitcnt vmcnt(0)
	buffer_inv sc1
	v_mbcnt_lo_u32_b32 v1, s8, 0
	v_mbcnt_hi_u32_b32 v1, s9, v1
	v_cmp_eq_u32_e32 vcc, 0, v1
	s_and_saveexec_b64 s[10:11], vcc
	s_cbranch_execz .LBB0_802
	s_bcnt1_i32_b64 s3, s[8:9]
	v_mov_b32_e32 v2, 0x2303000
	v_mov_b32_e32 v3, s3
	global_atomic_add v2, v2, v3, s[70:71] offset:1024 sc0

; __device__ __forceinline__ unsigned xb_ld(unsigned* p)              { return __hip_atomic_load(p, __ATOMIC_RELAXED, __HIP_MEMORY_SCOPE_AGENT); }
; __device__ __forceinline__ unsigned xb_add(unsigned* p, unsigned v) { return __hip_atomic_fetch_add(p, v, __ATOMIC_RELAXED, __HIP_MEMORY_SCOPE_AGENT); }
; #define XB_SPIN(cond, bar) do { unsigned _sp = 0; while (cond) { __builtin_amdgcn_s_sleep(1); \
;     if ((++_sp & 255u) == 0u) { if (xb_ld(&(bar)[XB_TMO])) break; if (_sp > XB_SPIN_CAP) { atomicAdd(&(bar)[XB_TMO], 1u); break; } } } } while (0)
; __device__ __forceinline__ void xcd_barrier(const XcdBarrier& b) {
;     ...
;             else XB_SPIN(xb_ld(&bar[XB_TOPGEN]) == tg, bar);
;             __builtin_amdgcn_fence(__ATOMIC_ACQUIRE, "agent");
;             xb_add(&bar[XB_XGEN(b.x)], 1u);
.LBB0_816:
	s_or_b64 exec, exec, s[8:9]
	s_mov_b64 s[8:9], exec
	v_mbcnt_lo_u32_b32 v0, s8, 0
	v_mbcnt_hi_u32_b32 v0, s9, v0
	v_cmp_eq_u32_e32 vcc, 0, v0
	s_waitcnt vmcnt(0)
	s_and_saveexec_b64 s[10:11], vcc
	s_cbranch_execz .LBB0_818
	s_bcnt1_i32_b64 s3, s[8:9]
	v_mov_b32_e32 v0, 0x2000
	v_mov_b32_e32 v1, s3
	global_atomic_add v0, v1, s[6:7] offset:1024
